# static s_setprio 1 for waves 4-7 during the attention phase (reset to 0 after)
# speedup vs baseline: 1.0189x; 1.0189x over previous
; __global__ void __launch_bounds__(NWAVES * 64, 2) fwd_megakernel(Params P) {
;     ...
;     for (int L = vcu; L < 2304; L += G) {
;         int diff, s, head, qb; attn_decode(L, diff, s, head, qb);
;         const float sref = *(const float*)(ws + WS_LAM + 4);
.LBB0_488:
	s_or_b64 exec, exec, s[4:5]
	s_cmpk_gt_i32 s3, 0x8ff
	s_waitcnt lgkmcnt(0)
	s_barrier
	s_cbranch_scc1 .LBB0_634
	v_readlane_b32 s4, v254, 18
	v_readlane_b32 s18, v254, 32
	v_readlane_b32 s5, v254, 19
	v_readlane_b32 s19, v254, 33
	s_add_u32 s4, s18, 0x15100000
	s_addc_u32 s5, s19, 0
	s_add_u32 s52, s18, 0x18100000
	s_addc_u32 s53, s19, 0
	s_add_u32 s61, s18, 0x1b100000
	v_readlane_b32 s10, v254, 24
	s_addc_u32 s66, s19, 0
	v_readlane_b32 s11, v254, 25
	s_add_u32 s10, s18, 0x28000
	v_readlane_b32 s6, v254, 20
	v_readlane_b32 s7, v254, 21
	v_readlane_b32 s8, v254, 22
	v_readlane_b32 s9, v254, 23
	v_readlane_b32 s12, v254, 26
	v_readlane_b32 s13, v254, 27
	v_readlane_b32 s14, v254, 28
	v_readlane_b32 s15, v254, 29
	v_readlane_b32 s16, v254, 30
	v_readlane_b32 s17, v254, 31
	v_writelane_b32 v254, s4, 43
	s_addc_u32 s11, s19, 0
	s_mov_b32 s15, 0
	v_writelane_b32 v254, s5, 44
	s_add_u32 s4, s18, 0x28004
	s_addc_u32 s5, s19, 0
	v_writelane_b32 v254, s4, 45
	v_mov_b32_e32 v0, 0
	s_mov_b32 s62, 0xf800000
	v_writelane_b32 v254, s5, 46
	s_add_u32 s4, s18, 0x4900000
	v_writelane_b32 v254, s4, 47
	s_addc_u32 s4, s19, 0
	v_writelane_b32 v254, s4, 48
	s_add_u32 s4, s18, 0x1e100000
	v_writelane_b32 v254, s4, 49
	s_addc_u32 s4, s19, 0
	v_writelane_b32 v254, s4, 50
	s_add_u32 s4, s18, 0x1b110000
	v_writelane_b32 v254, s4, 51
	s_addc_u32 s4, s19, 0
	v_writelane_b32 v254, s4, 52
	s_add_i32 s4, 0, 0x1ed00
	v_mov_b32_e32 v232, 0x260
	s_movk_i32 s17, 0x4000
	s_movk_i32 s33, 0x100
	s_add_i32 s65, 0, 0x14000
	s_add_i32 s68, 0, 0x1e800
	v_writelane_b32 v254, s4, 53
	v_mov_b32_e32 v233, 0x3c23d70a
	v_mov_b32_e32 v234, 0x358637bd
	s_movk_i32 s70, 0x7fff
	s_mov_b32 s71, 0x41000000
	v_mbcnt_hi_u32_b32 v235, -1, v231
	v_writelane_b32 v254, s1, 54
	v_readfirstlane_b32 s98, v230
	s_lshr_b32 s98, s98, 6
	s_cmp_ge_u32 s98, 4
	s_cbranch_scc0 .Lprio_skip
	s_setprio 1
.Lprio_skip:
	s_branch .LBB0_493

; __device__ __forceinline__ unsigned xb_ld(unsigned* p)              { return __hip_atomic_load(p, __ATOMIC_RELAXED, __HIP_MEMORY_SCOPE_AGENT); }
; __device__ __forceinline__ void xcd_barrier_complete(unsigned* bar, unsigned x, unsigned& nloc, unsigned& nx) {
;     const unsigned G = gridDim.x * gridDim.y * gridDim.z;
;     unsigned sum, cnt, mine, sp = 0u;
;     for (;;) {
;         sum = 0u; cnt = 0u; mine = 0u;
; #pragma unroll
;         for (unsigned j = 0; j < 16; ++j) { const unsigned c = xb_ld(&bar[XB_XCNT(j)]); sum += c; cnt += (c > 0u) ? 1u : 0u; mine = (j == x) ? c : mine; }
; __device__ __forceinline__ void xcd_barrier(const XcdBarrier& b) {
;     asm volatile("s_waitcnt vmcnt(0)" ::: "memory");
;     __syncthreads();
;     if (threadIdx.x == 0) {
;         unsigned* bar = b.bar;
;         __builtin_amdgcn_s_waitcnt(0);
;         unsigned nloc = b.st[0], nx = b.st[1];
;         if (nloc == 0u) { xcd_barrier_complete(bar, b.x, nloc, nx); b.st[0] = nloc; b.st[1] = nx; }
.LBB0_634:
	s_setprio 0
	s_waitcnt vmcnt(0)
	s_waitcnt vmcnt(63) expcnt(7) lgkmcnt(15)
	s_barrier
	s_mov_b64 s[4:5], exec
	v_readlane_b32 s0, v254, 37
	v_readlane_b32 s1, v254, 38
	v_readlane_b32 s16, v254, 18
	s_and_b64 s[0:1], s[4:5], s[0:1]
	v_readlane_b32 s18, v254, 20
	v_readlane_b32 s19, v254, 21
	v_readlane_b32 s20, v254, 22
	v_readlane_b32 s21, v254, 23
	v_readlane_b32 s26, v254, 28
	v_readlane_b32 s27, v254, 29
	v_readlane_b32 s28, v254, 30
	v_readlane_b32 s29, v254, 31
	v_readlane_b32 s30, v254, 32
	v_readlane_b32 s31, v254, 33
	v_readlane_b32 s17, v254, 19
	v_readlane_b32 s22, v254, 24
	v_readlane_b32 s23, v254, 25
	v_readlane_b32 s24, v254, 26
	v_readlane_b32 s25, v254, 27
	s_mov_b64 exec, s[0:1]
	s_cbranch_execz .LBB0_686
	s_add_i32 s0, 0, 0x20000
	v_mov_b32_e32 v0, s0
	s_waitcnt vmcnt(0) expcnt(0) lgkmcnt(0)
	ds_read_b32 v2, v0
	s_add_i32 s0, 0, 0x20004
	v_mov_b32_e32 v0, s0
	ds_read_b32 v0, v0
	s_waitcnt lgkmcnt(1)
	v_cmp_ne_u32_e32 vcc, 0, v2
	s_cbranch_vccnz .LBB0_650
	s_add_u32 s6, s30, 0x80200
	s_addc_u32 s7, s31, 0
	s_add_u32 s8, s30, 0x80400
	s_addc_u32 s9, s31, 0
	s_add_u32 s10, s30, 0x80500
	s_addc_u32 s11, s31, 0
	s_add_u32 s12, s30, 0x80600
	s_addc_u32 s13, s31, 0
	s_add_u32 s14, s30, 0x80700
	s_addc_u32 s15, s31, 0
	s_add_u32 s40, s30, 0x80800
	s_addc_u32 s41, s31, 0
	s_add_u32 s42, s30, 0x80900
	s_addc_u32 s43, s31, 0
	s_add_u32 s44, s30, 0x80a00
	s_addc_u32 s45, s31, 0
	s_add_u32 s46, s30, 0x80b00
	s_addc_u32 s47, s31, 0
	s_add_u32 s48, s30, 0x80c00
	s_addc_u32 s49, s31, 0
	s_add_u32 s50, s30, 0x80d00
	s_addc_u32 s51, s31, 0
	s_add_u32 s52, s30, 0x80e00
	s_addc_u32 s53, s31, 0
	s_add_u32 s54, s30, 0x80f00
	s_addc_u32 s55, s31, 0
	s_add_u32 s56, s30, 0x81000
	s_addc_u32 s57, s31, 0
	s_add_u32 s58, s30, 0x81100
	s_addc_u32 s59, s31, 0
	s_add_u32 s60, s30, 0x81200
	v_readlane_b32 s0, v254, 0
	s_addc_u32 s61, s31, 0
	s_mul_i32 s0, s91, s0
	s_add_u32 s62, s30, 0x81300
	s_mul_i32 s0, s0, s90
	s_addc_u32 s63, s31, 0
	s_mov_b32 s1, 1
	v_mov_b32_e32 v16, 0
	s_branch .LBB0_638
